# P0b modulate loop: two elements per trip, all twelve loads in flight before the first use (was one element, latency bound)
# speedup vs baseline: 1.0044x; 1.0007x over previous
; __device__ __forceinline__ unsigned cvtpk(float lo, float hi) { f32x2_t v = {lo, hi}; bf16x2_t b = __builtin_convertvector(v, bf16x2_t); return __builtin_bit_cast(unsigned, b); }
; __device__ __forceinline__ int tid_fresh() { int t = threadIdx.x; asm volatile("" : "+v"(t)); return t; }
; __device__ __forceinline__ void p_modulate(const Args& A) {
;     const float* mod = (const float*)(A.ws + WS_MOD);
;     bf16* U = (bf16*)(A.ws + WS_U);
;     const size_t n8 = (size_t)MT * 1024 / 8;
;     const int tidm = tid_fresh();
;     for (size_t e = (size_t)blockIdx.x * 512 + tidm; e < n8; e += (size_t)gridDim.x * 512) {
;         const int row = (int)(e >> 7), c8 = (int)(e & 127) * 8, b = row >> 13;
;         const f32x4 x0 = *(const f32x4*)(A.x + (size_t)row * 1024 + c8), x1 = *(const f32x4*)(A.x + (size_t)row * 1024 + c8 + 4);
;         const float* mb = mod + b * 3072 + c8;
;         const f32x4 sh0 = *(const f32x4*)(mb), sh1 = *(const f32x4*)(mb + 4), sc0 = *(const f32x4*)(mb + 1024), sc1 = *(const f32x4*)(mb + 1028);
;         const f32x4 u0 = x0 * (sc0 + 1.0f) + sh0, u1 = x1 * (sc1 + 1.0f) + sh1;
;         u32x4 o; o.x = cvtpk(u0[0], u0[1]); o.y = cvtpk(u0[2], u0[3]); o.z = cvtpk(u1[0], u1[1]); o.w = cvtpk(u1[2], u1[3]);
;         *(u32x4*)(U + (size_t)row * 1024 + c8) = o;
;     }
.LBB0_98:
	v_readlane_b32 s4, v254, 0
	v_readlane_b32 s5, v254, 1
	s_cmp_gt_i32 s4, 1
	s_cselect_b64 s[0:1], -1, 0
	s_cmp_lt_i32 s5, 2
	s_cselect_b64 s[4:5], -1, 0
	s_or_b64 s[0:1], s[0:1], s[4:5]
	s_and_b64 vcc, exec, s[0:1]
	v_readlane_b32 s6, v254, 2
	v_readlane_b32 s7, v254, 3
	s_cbranch_vccnz .LBB0_103
	v_and_b32_e32 v4, 0x3ff, v0
	s_mov_b32 s3, 0
	s_lshl_b64 s[4:5], s[2:3], 9
	v_ashrrev_i32_e32 v5, 31, v4
	v_lshl_add_u64 v[2:3], s[4:5], 0, v[4:5]
	s_mov_b64 s[4:5], 0x400000
	v_cmp_gt_u64_e32 vcc, s[4:5], v[2:3]
	s_and_saveexec_b64 s[4:5], vcc
	s_cbranch_execz .LBB0_102
	s_add_u32 s6, s66, 0x2c40000
	s_addc_u32 s7, s67, 0
	s_mov_b32 s27, s3
	s_lshl_b64 s[10:11], s[2:3], 12
	s_lshl_b64 s[8:9], s[26:27], 9
	v_lshl_add_u64 v[4:5], v[4:5], 3, s[10:11]
	s_lshl_b64 s[10:11], s[26:27], 12
	s_mov_b64 s[12:13], 0
	v_mov_b32_e32 v7, 0
	s_mov_b64 s[14:15], 0x1000
	s_movk_i32 s3, 0x1000
	s_mov_b64 s[16:17], 0x3fffff
	s_cmp_lg_u32 s26, 0x100
	s_cbranch_scc1 .LBB0_101
	v_mov_b32_e32 v47, 0
.Lp0b_loop:
	v_alignbit_b32 v6, v3, v2, 7
	v_lshrrev_b32_e32 v8, 13, v6
	v_and_b32_e32 v38, 0x3f8, v4
	v_mov_b32_e32 v9, v7
	v_mul_u32_u24_e32 v8, 0xc00, v8
	v_lshrrev_b64 v[32:33], 7, v[2:3]
	v_lshlrev_b32_e32 v6, 2, v38
	v_lshl_add_u64 v[18:19], v[8:9], 2, s[66:67]
	v_lshlrev_b64 v[10:11], 12, v[32:33]
	v_lshl_add_u64 v[34:35], v[18:19], 0, v[6:7]
	v_lshl_add_u64 v[10:11], s[68:69], 0, v[10:11]
	v_add_co_u32_e32 v20, vcc, s3, v34
	v_lshl_add_u64 v[16:17], v[10:11], 0, v[6:7]
	s_nop 0
	v_addc_co_u32_e32 v21, vcc, 0, v35, vcc
	global_load_dwordx4 v[8:11], v[16:17], off offset:16
	global_load_dwordx4 v[12:15], v[16:17], off
	v_lshl_add_u64 v[36:37], v[34:35], 0, s[14:15]
	global_load_dwordx4 v[16:19], v[34:35], off
	s_nop 0
	global_load_dwordx4 v[20:23], v[20:21], off
	s_nop 0
	global_load_dwordx4 v[24:27], v[36:37], off offset:16
	global_load_dwordx4 v[28:31], v[34:35], off offset:16
	v_lshlrev_b64 v[32:33], 11, v[32:33]
	v_lshl_add_u64 v[32:33], s[6:7], 0, v[32:33]
	v_lshlrev_b32_e32 v6, 1, v38
	v_lshl_add_u64 v[32:33], v[32:33], 0, v[6:7]
	v_lshl_add_u64 v[2:3], v[2:3], 0, s[8:9]
	v_lshl_add_u64 v[4:5], v[4:5], 0, s[10:11]
	v_alignbit_b32 v46, v3, v2, 7
	v_lshrrev_b32_e32 v48, 13, v46
	v_and_b32_e32 v78, 0x3f8, v4
	v_mov_b32_e32 v49, v7
	v_mul_u32_u24_e32 v48, 0xc00, v48
	v_lshrrev_b64 v[72:73], 7, v[2:3]
	v_lshlrev_b32_e32 v46, 2, v78
	v_lshl_add_u64 v[58:59], v[48:49], 2, s[66:67]
	v_lshlrev_b64 v[50:51], 12, v[72:73]
	v_lshl_add_u64 v[74:75], v[58:59], 0, v[46:47]
	v_lshl_add_u64 v[50:51], s[68:69], 0, v[50:51]
	v_add_co_u32_e32 v60, vcc, s3, v74
	v_lshl_add_u64 v[56:57], v[50:51], 0, v[46:47]
	s_nop 0
	v_addc_co_u32_e32 v61, vcc, 0, v75, vcc
	global_load_dwordx4 v[48:51], v[56:57], off offset:16
	global_load_dwordx4 v[52:55], v[56:57], off
	v_lshl_add_u64 v[76:77], v[74:75], 0, s[14:15]
	global_load_dwordx4 v[56:59], v[74:75], off
	s_nop 0
	global_load_dwordx4 v[60:63], v[60:61], off
	s_nop 0
	global_load_dwordx4 v[64:67], v[76:77], off offset:16
	global_load_dwordx4 v[68:71], v[74:75], off offset:16
	v_lshlrev_b64 v[72:73], 11, v[72:73]
	v_lshl_add_u64 v[72:73], s[6:7], 0, v[72:73]
	v_lshlrev_b32_e32 v46, 1, v78
	v_lshl_add_u64 v[72:73], v[72:73], 0, v[46:47]
	v_lshl_add_u64 v[2:3], v[2:3], 0, s[8:9]
	v_lshl_add_u64 v[4:5], v[4:5], 0, s[10:11]
	v_cmp_lt_u64_e32 vcc, s[16:17], v[2:3]
	s_or_b64 s[12:13], vcc, s[12:13]
	s_waitcnt vmcnt(8)
	v_pk_add_f32 v[22:23], v[22:23], 1.0 op_sel_hi:[1,0]
	v_pk_add_f32 v[20:21], v[20:21], 1.0 op_sel_hi:[1,0]
	s_waitcnt vmcnt(7)
	v_pk_add_f32 v[26:27], v[26:27], 1.0 op_sel_hi:[1,0]
	v_pk_add_f32 v[24:25], v[24:25], 1.0 op_sel_hi:[1,0]
	v_pk_fma_f32 v[14:15], v[14:15], v[22:23], v[18:19]
	v_pk_fma_f32 v[12:13], v[12:13], v[20:21], v[16:17]
	s_waitcnt vmcnt(6)
	v_pk_fma_f32 v[16:17], v[10:11], v[26:27], v[30:31]
	v_pk_fma_f32 v[10:11], v[8:9], v[24:25], v[28:29]
	v_cvt_pk_bf16_f32 v8, v12, v13
	v_cvt_pk_bf16_f32 v9, v14, v15
	v_cvt_pk_bf16_f32 v10, v10, v11
	v_cvt_pk_bf16_f32 v11, v16, v17
	global_store_dwordx4 v[32:33], v[8:11], off
	s_waitcnt vmcnt(3)
	v_pk_add_f32 v[62:63], v[62:63], 1.0 op_sel_hi:[1,0]
	v_pk_add_f32 v[60:61], v[60:61], 1.0 op_sel_hi:[1,0]
	s_waitcnt vmcnt(2)
	v_pk_add_f32 v[66:67], v[66:67], 1.0 op_sel_hi:[1,0]
	v_pk_add_f32 v[64:65], v[64:65], 1.0 op_sel_hi:[1,0]
	v_pk_fma_f32 v[54:55], v[54:55], v[62:63], v[58:59]
	v_pk_fma_f32 v[52:53], v[52:53], v[60:61], v[56:57]
	s_waitcnt vmcnt(1)
	v_pk_fma_f32 v[56:57], v[50:51], v[66:67], v[70:71]
	v_pk_fma_f32 v[50:51], v[48:49], v[64:65], v[68:69]
	v_cvt_pk_bf16_f32 v48, v52, v53
	v_cvt_pk_bf16_f32 v49, v54, v55
	v_cvt_pk_bf16_f32 v50, v50, v51
	v_cvt_pk_bf16_f32 v51, v56, v57
	global_store_dwordx4 v[72:73], v[48:51], off
	s_andn2_b64 exec, exec, s[12:13]
	s_cbranch_execnz .Lp0b_loop
	s_branch .LBB0_102
